# pp GEMM: one tile per workgroup (instead of two on the tail half), on top of the no-setprio stack
# baseline (speedup 1.0000x reference)
.LBB0_557:
	v_readlane_b32 s0, v254, 32
	v_readlane_b32 s1, v254, 33
	s_andn2_b64 vcc, exec, s[0:1]
	s_cbranch_vccnz .LBB0_576
	s_add_i32 s0, s54, 0xffffff80
	s_cmpk_gt_i32 s54, 0x7f
	s_cselect_b32 s4, s0, 0x100
	s_cmpk_eq_i32 s59, 0x100
	s_cselect_b64 s[0:1], -1, 0
	s_and_b64 s[2:3], s[0:1], exec
	s_mov_b32 s5, s54
	s_cmpk_gt_i32 s5, 0xff
	s_waitcnt vmcnt(0)
	v_mov_b32_e32 v0, v242
	s_cbranch_scc1 .LBB0_576
	v_lshl_add_u32 v1, v0, 4, s89
	v_add_u32_e32 v2, 0x2000, v1
	v_ashrrev_i32_e32 v3, 31, v2
	v_lshrrev_b32_e32 v3, 22, v3
	v_add_u32_e32 v3, v2, v3
	v_ashrrev_i32_e32 v3, 10, v3
	s_and_b64 s[2:3], s[56:57], exec
	v_mul_i32_i24_e32 v4, 0x400, v3
	s_cselect_b32 s2, 0x400000, 0
	v_sub_u32_e32 v2, v2, v4
	s_add_u32 s2, s80, s2
	v_lshrrev_b32_e32 v4, 4, v2
	s_addc_u32 s3, s81, 0
	v_bitop3_b32 v2, v4, v2, 32 bitop3:0x6c
	s_add_u32 s24, s2, 0x1ff00000
	v_ashrrev_i32_e32 v4, 31, v2
	s_addc_u32 s25, s3, 0
	v_lshrrev_b32_e32 v4, 26, v4
	s_and_b64 s[2:3], s[56:57], exec
	v_add_u32_e32 v4, v2, v4
	v_lshlrev_b32_e32 v6, 3, v3
	s_cselect_b32 s2, 0x100000, 0
	v_ashrrev_i32_e32 v5, 6, v4
	v_and_b32_e32 v6, -16, v6
	v_and_b32_e32 v4, 0xffc0, v4
	s_add_u32 s2, s80, s2
	v_add_u32_e32 v6, v5, v6
	v_sub_u32_e32 v2, v2, v4
	s_addc_u32 s3, s81, 0
	v_and_b32_e32 v5, 3, v5
	s_mov_b32 s7, 0x7fffe0
	v_lshrrev_b32_e32 v7, 2, v6
	v_lshlrev_b32_e32 v8, 1, v6
	v_lshrrev_b16_e32 v4, 7, v2
	s_add_u32 s26, s2, 0x17900000
	v_and_or_b32 v5, v6, s7, v5
	v_and_b32_e32 v7, 4, v7
	v_and_b32_e32 v8, 24, v8
	v_and_b32_e32 v4, 1, v4
	s_addc_u32 s27, s3, 0
	s_ashr_i32 s6, s5, 31
	v_or3_b32 v5, v5, v7, v8
	v_add_u16_e32 v2, v2, v4
	v_mov_b32_e32 v8, 1
	s_lshr_b32 s2, s6, 29
	v_lshlrev_b32_e32 v3, 5, v3
	v_ashrrev_i16_sdwa v2, v8, sext(v2) dst_sel:DWORD dst_unused:UNUSED_PAD src0_sel:DWORD src1_sel:BYTE_0
	s_add_i32 s2, s5, s2
	v_and_b32_e32 v3, 32, v3
	v_bfe_i32 v2, v2, 0, 16
	s_ashr_i32 s3, s2, 3
	s_and_b32 s2, s2, -8
	v_add_lshl_u32 v2, v3, v2, 1
	s_sub_i32 s2, s5, s2
	v_lshl_add_u32 v128, v5, 9, v2
	v_lshl_add_u32 v130, v6, 9, v2
	v_ashrrev_i32_e32 v2, 31, v1
	s_lshl_b32 s4, s2, 5
	v_lshrrev_b32_e32 v2, 22, v2
	s_cmp_lt_i32 s2, 0
	s_mul_i32 s2, s2, 33
	v_add_u32_e32 v2, v1, v2
	v_ashrrev_i32_e32 v2, 10, v2
	s_cselect_b32 s2, s2, s4
	v_mul_i32_i24_e32 v3, 0x400, v2
	s_add_i32 s2, s2, s3
	v_sub_u32_e32 v1, v1, v3
	s_ashr_i32 s3, s2, 31
	v_lshrrev_b32_e32 v3, 4, v1
	s_lshr_b32 s3, s3, 27
	v_bitop3_b32 v1, v3, v1, 32 bitop3:0x6c
	s_add_i32 s3, s2, s3
	v_ashrrev_i32_e32 v3, 31, v1
	s_ashr_i32 s4, s3, 5
	s_and_b32 s3, s3, 0xffe0
	v_lshrrev_b32_e32 v3, 26, v3
	s_sub_i32 s2, s2, s3
	v_add_u32_e32 v3, v1, v3
	v_lshlrev_b32_e32 v5, 3, v2
	s_bfe_i32 s3, s2, 0x80000
	v_ashrrev_i32_e32 v4, 6, v3
	v_and_b32_e32 v5, -16, v5
	s_bfe_u32 s3, s3, 0x2000d
	v_add_u32_e32 v5, v4, v5
	v_and_b32_e32 v4, 3, v4
	s_add_i32 s3, s2, s3
	v_and_or_b32 v4, v5, s7, v4
	s_lshl_b32 s7, s4, 2
	s_bfe_i32 s4, s3, 0x80000
	s_and_b32 s3, s3, 0xfc
	s_sub_i32 s2, s2, s3
	s_sext_i32_i16 s4, s4
	s_sext_i32_i8 s2, s2
	v_and_b32_e32 v3, 0xc0, v3
	s_lshr_b32 s4, s4, 2
	s_add_i32 s12, s7, s2
	v_sub_u32_e32 v1, v1, v3
	s_ashr_i32 s13, s12, 31
	s_bfe_i64 s[8:9], s[4:5], 0x100000
	v_lshrrev_b32_e32 v6, 2, v5
	v_lshlrev_b32_e32 v7, 1, v5
	v_lshlrev_b32_e32 v2, 5, v2
	v_ashrrev_i16_sdwa v1, v8, sext(v1) dst_sel:DWORD dst_unused:UNUSED_PAD src0_sel:DWORD src1_sel:BYTE_0
	s_lshl_b64 s[2:3], s[12:13], 17
	s_lshl_b64 s[8:9], s[8:9], 17
	v_and_b32_e32 v6, 4, v6
	v_and_b32_e32 v7, 24, v7
	v_and_b32_e32 v2, 32, v2
	v_bfe_i32 v1, v1, 0, 16
	s_add_u32 s18, s26, s8
	v_or3_b32 v4, v4, v6, v7
	v_add_lshl_u32 v1, v2, v1, 1
	s_addc_u32 s19, s27, s9
	s_add_i32 s13, s89, 0
	v_lshl_add_u32 v184, v4, 9, v1
	s_add_i32 m0, s13, 0x10000
	v_lshl_add_u32 v132, v5, 9, v1
	global_load_lds_dwordx4 v184, s[18:19]
	s_add_i32 m0, s13, 0x12000
	s_add_u32 s8, s18, 0x10000
	global_load_lds_dwordx4 v128, s[18:19]
	s_addc_u32 s9, s19, 0
	s_add_i32 m0, s13, 0x14000
	s_nop 0
	global_load_lds_dwordx4 v184, s[8:9]
	s_add_i32 m0, s13, 0x16000
	s_add_u32 s16, s24, s2
	s_addc_u32 s17, s25, s3
	s_add_i32 s28, s13, 0x2000
	global_load_lds_dwordx4 v128, s[8:9]
	s_mov_b32 m0, s13
	s_add_u32 s2, s16, 0x10000
	global_load_lds_dwordx4 v132, s[16:17]
	s_mov_b32 m0, s28
	s_addc_u32 s3, s17, 0
	s_add_i32 s29, s13, 0x4000
	global_load_lds_dwordx4 v130, s[16:17]
	s_mov_b32 m0, s29
	s_add_i32 s30, s13, 0x6000
	global_load_lds_dwordx4 v132, s[2:3]
	s_mov_b32 m0, s30
	v_readlane_b32 s8, v254, 4
	global_load_lds_dwordx4 v130, s[2:3]
	v_readlane_b32 s9, v254, 5
	s_andn2_b64 vcc, exec, s[8:9]
	s_nop 0
	v_cndmask_b32_e64 v1, 0, 1, s[8:9]
	v_cmp_ne_u32_e64 s[2:3], 1, v1
	s_cbranch_vccnz .LBB0_561
	s_barrier
.LBB0_561:
	v_lshl_add_u64 v[2:3], s[18:19], 0, v[184:185]
	v_mov_b32_e32 v129, v185
	s_and_b64 s[0:1], s[0:1], exec
	v_lshl_add_u64 v[4:5], s[18:19], 0, v[128:129]
	v_mov_b32_e32 v133, v185
	s_mov_b32 s31, s59
	v_lshl_add_u64 v[2:3], v[2:3], 0, s[96:97]
	s_add_i32 m0, s13, 0x18000
	v_lshl_add_u64 v[6:7], s[16:17], 0, v[132:133]
	v_mov_b32_e32 v131, v185
	s_ashr_i32 s34, s31, 31
	s_waitcnt vmcnt(2)
	s_barrier
	global_load_lds_dwordx4 v[2:3], off
	v_lshl_add_u64 v[2:3], v[4:5], 0, s[96:97]
	s_add_i32 m0, s13, 0x1a000
	s_add_i32 s35, s13, 0x8000
	s_add_i32 s36, s13, 0xa000
	v_lshl_add_u64 v[8:9], s[16:17], 0, v[130:131]
	global_load_lds_dwordx4 v[2:3], off
	v_lshl_add_u64 v[2:3], v[6:7], 0, s[96:97]
	s_mov_b32 m0, s35
	s_add_u32 s0, s18, 0x10080
	global_load_lds_dwordx4 v[2:3], off
	v_lshl_add_u64 v[2:3], v[8:9], 0, s[96:97]
	s_mov_b32 m0, s36
	s_addc_u32 s1, s19, 0
	global_load_lds_dwordx4 v[2:3], off
	v_lshl_add_u64 v[2:3], s[0:1], 0, v[184:185]
	s_add_i32 m0, s13, 0x1c000
	v_and_b32_e32 v1, 15, v0
	global_load_lds_dwordx4 v[2:3], off
	v_lshl_add_u64 v[2:3], s[0:1], 0, v[128:129]
	s_add_i32 m0, s13, 0x1e000
	v_and_b32_e32 v5, 48, v0
	global_load_lds_dwordx4 v[2:3], off
	v_or_b32_e32 v2, s33, v1
	v_lshlrev_b32_e32 v4, 6, v2
	s_movk_i32 s0, 0x3c0
	v_ashrrev_i32_e32 v3, 6, v0
	v_and_or_b32 v4, v4, s0, v5
	v_readlane_b32 s0, v254, 2
	v_lshlrev_b32_e32 v2, 2, v2
	v_and_b32_e32 v2, 32, v2
	v_lshl_add_u32 v6, v3, 10, s0
	v_readlane_b32 s0, v254, 8
	v_lshlrev_b32_e32 v0, 2, v0
	s_waitcnt vmcnt(6)
	v_bitop3_b32 v2, v4, v6, v2 bitop3:0xde
	v_lshl_or_b32 v1, v1, 6, v5
	v_add_lshl_u32 v3, v3, s0, 10
	v_and_b32_e32 v0, 32, v0
	s_add_u32 s0, s31, s5
	s_sext_i32_i8 s37, s4
	v_bitop3_b32 v134, v1, v3, v0 bitop3:0xde
	s_addc_u32 s1, s34, s6
	v_add_u32_e32 v135, 0, v2
	s_barrier
	s_branch .LBB0_564
